# branch-gate tensor stored as 16x16 fragment tiles: mix-in gates epilogue stores and up-proj gate loads are contiguous 512 B per wave instruction (on v057, without the rope-LDS change)
# speedup vs baseline: 1.0196x; 1.0196x over previous
.LBB0_272:
	s_ashr_i32 s2, s64, 5
	s_lshr_b32 s3, s2, 29
	s_add_i32 s3, s2, s3
	s_ashr_i32 s6, s3, 3
	s_and_b32 s3, s3, -8
	s_sub_i32 s2, s2, s3
	s_lshl_b32 s3, s64, 3
	s_and_b32 s3, s3, 56
	s_lshl_b32 s29, s6, 2
	s_bfe_u32 s28, s64, 0x20003
	s_add_i32 s3, s29, s3
	s_or_b32 s24, s3, s28
	s_ashr_i32 s25, s24, 31
	s_and_b32 s0, s63, 56
	s_lshl_b64 s[6:7], s[24:25], 18
	s_add_u32 s65, s14, s6
	s_addc_u32 s66, s15, s7
	s_ashr_i32 s3, s2, 31
	s_lshl_b64 s[8:9], s[2:3], 17
	s_add_u32 s67, s36, s8
	s_addc_u32 s68, s37, s9
	s_cmp_eq_u32 s64, s79
	s_cselect_b64 s[12:13], -1, 0
	s_add_i32 s64, s64, s72
	s_cmpk_gt_i32 s64, 0x1ff
	s_cselect_b64 s[6:7], -1, 0
	s_ashr_i32 s22, s64, 5
	s_lshr_b32 s23, s22, 29
	s_add_i32 s23, s22, s23
	s_ashr_i32 s25, s23, 3
	s_and_b32 s23, s23, -8
	s_sub_i32 s22, s22, s23
	s_lshl_b32 s23, s64, 3
	s_and_b32 s23, s23, 56
	s_lshl_b32 s25, s25, 2
	s_bfe_u32 s3, s64, 0x20003
	s_add_i32 s25, s25, s23
	s_or_b32 s26, s25, s3
	s_ashr_i32 s27, s26, 31
	s_lshl_b64 s[26:27], s[26:27], 18
	s_add_u32 s25, s61, s26
	s_addc_u32 s26, s62, s27
	s_ashr_i32 s23, s22, 31
	s_lshl_b64 s[22:23], s[22:23], 17
	v_mov_b32_e32 v2, v190
	s_add_u32 s27, s36, s22
	s_addc_u32 s70, s37, s23
	s_lshl_b32 s2, s2, 7
	s_lshl_b32 s98, s2, 5
	s_add_u32 s98, s30, s98
	s_addc_u32 s99, s31, 0
	v_ashrrev_i32_e32 v0, 1, v2
	s_ashr_i32 s3, s2, 31
	v_and_b32_e32 v0, 0xffffff80, v0
	s_lshl_b64 s[22:23], s[2:3], 1
	v_lshl_add_u32 v0, s24, 8, v0
	s_add_u32 s2, s30, s22
	v_and_or_b32 v96, v2, 15, v0
	v_lshrrev_b32_e32 v0, 1, v2
	s_addc_u32 s3, s31, s23
	v_and_b32_e32 v98, 0x60, v0
	s_cmpk_lt_i32 s64, 0x200
	v_lshlrev_b32_e32 v144, 1, v98
	s_movk_i32 s24, 0x1800
	v_or_b32_e32 v100, 16, v96
	v_or_b32_e32 v90, 32, v96
	v_or_b32_e32 v88, 48, v96
	v_or_b32_e32 v82, 64, v96
	v_or_b32_e32 v76, 0x50, v96
	v_or_b32_e32 v70, 0x60, v96
	v_or_b32_e32 v64, 0x70, v96
	s_waitcnt lgkmcnt(0)
	v_lshl_add_u64 v[0:1], s[2:3], 0, v[144:145]
	s_cselect_b32 s70, s70, 0
	s_cselect_b32 s71, s27, 0
	s_cselect_b32 s72, s26, 0
	s_cselect_b32 s73, s25, 0
	v_and_b32_e32 v66, 0xfffffff0, v96
	v_mad_i64_i32 v[118:119], s[2:3], v66, s24, 0
	v_and_b32_e32 v66, 0xfffffff0, v100
	v_mad_i64_i32 v[120:121], s[2:3], v66, s24, 0
	v_and_b32_e32 v66, 0xfffffff0, v90
	v_mad_i64_i32 v[126:127], s[2:3], v66, s24, 0
	v_and_b32_e32 v66, 0xfffffff0, v88
	v_mad_i64_i32 v[128:129], s[2:3], v66, s24, 0
	v_and_b32_e32 v66, 0xfffffff0, v82
	v_mad_i64_i32 v[134:135], s[2:3], v66, s24, 0
	v_and_b32_e32 v66, 0xfffffff0, v76
	v_mad_i64_i32 v[136:137], s[2:3], v66, s24, 0
	v_and_b32_e32 v66, 0xfffffff0, v70
	v_mad_i64_i32 v[142:143], s[2:3], v66, s24, 0
	v_and_b32_e32 v66, 0xfffffff0, v64
	v_mad_i64_i32 v[154:155], s[2:3], v66, s24, 0
	s_add_u32 s24, s14, s8
	s_addc_u32 s25, s15, s9
	s_add_i32 s0, s0, s29
	s_or_b32 s2, s0, s28
	v_lshrrev_b32_e32 v2, 2, v2
	s_ashr_i32 s3, s2, 31
	v_and_b32_e32 v106, 12, v2
	s_lshl_b64 s[2:3], s[2:3], 18
	v_lshlrev_b32_e32 v144, 1, v106
	s_add_u32 s74, s14, s2
	v_mov_b32_e32 v66, 0
	v_and_b32_e32 v112, 63, v190
	v_lshlrev_b32_e32 v112, 3, v112
	v_and_b32_e32 v113, 0xc0, v190
	v_lshl_add_u32 v144, v113, 4, v112
	v_lshl_add_u64 v[112:113], s[98:99], 0, v[144:145]
	s_mov_b32 s69, 0
	v_ashrrev_i32_e32 v97, 31, v96
	v_ashrrev_i32_e32 v101, 31, v100
	v_ashrrev_i32_e32 v91, 31, v90
	v_ashrrev_i32_e32 v89, 31, v88
	v_ashrrev_i32_e32 v83, 31, v82
	v_ashrrev_i32_e32 v77, 31, v76
	v_ashrrev_i32_e32 v71, 31, v70
	v_ashrrev_i32_e32 v65, 31, v64
	s_addc_u32 s75, s15, s3
	v_mov_b32_e32 v67, v66
	v_mov_b32_e32 v68, v66
	v_mov_b32_e32 v69, v66
	v_mov_b32_e32 v74, v66
	v_mov_b32_e32 v75, v66
	v_mov_b32_e32 v72, v66
	v_mov_b32_e32 v73, v66
	v_mov_b32_e32 v80, v66
	v_mov_b32_e32 v81, v66
	v_mov_b32_e32 v78, v66
	v_mov_b32_e32 v79, v66
	v_mov_b32_e32 v86, v66
	v_mov_b32_e32 v87, v66
	v_mov_b32_e32 v84, v66
	v_mov_b32_e32 v85, v66
	v_mov_b32_e32 v94, v66
	v_mov_b32_e32 v95, v66
	v_mov_b32_e32 v92, v66
	v_mov_b32_e32 v93, v66
	v_mov_b32_e32 v104, v66
	v_mov_b32_e32 v105, v66
	v_mov_b32_e32 v102, v66
	v_mov_b32_e32 v103, v66
	v_mov_b32_e32 v110, v66
	v_mov_b32_e32 v111, v66
	v_mov_b32_e32 v108, v66
	v_mov_b32_e32 v109, v66
	v_mov_b32_e32 v116, v66
	v_mov_b32_e32 v117, v66
	v_mov_b32_e32 v114, v66
	v_mov_b32_e32 v115, v66
	v_mov_b32_e32 v124, v66
	v_mov_b32_e32 v125, v66
	v_mov_b32_e32 v122, v66
	v_mov_b32_e32 v123, v66
	v_mov_b32_e32 v132, v66
	v_mov_b32_e32 v133, v66
	v_mov_b32_e32 v130, v66
	v_mov_b32_e32 v131, v66
	v_mov_b32_e32 v140, v66
	v_mov_b32_e32 v141, v66
	v_mov_b32_e32 v138, v66
	v_mov_b32_e32 v139, v66
	v_mov_b32_e32 v158, v66
	v_mov_b32_e32 v159, v66
	v_mov_b32_e32 v156, v66
	v_mov_b32_e32 v157, v66
	v_mov_b32_e32 v162, v66
	v_mov_b32_e32 v163, v66
	v_mov_b32_e32 v160, v66
	v_mov_b32_e32 v161, v66
	v_mov_b32_e32 v166, v66
	v_mov_b32_e32 v167, v66
	v_mov_b32_e32 v164, v66
	v_mov_b32_e32 v165, v66
	v_mov_b32_e32 v170, v66
	v_mov_b32_e32 v171, v66
	v_mov_b32_e32 v168, v66
	v_mov_b32_e32 v169, v66
	v_mov_b32_e32 v174, v66
	v_mov_b32_e32 v175, v66
	v_mov_b32_e32 v172, v66
	v_mov_b32_e32 v173, v66
	s_branch .LBB0_274
.LBB0_273:
	v_add_u32_e32 v144, v151, v182
	v_or_b32_e32 v146, 0x18000, v144
	v_add_u32_e32 v144, 0x18800, v144
	ds_read_b128 v[146:149], v146
	ds_read_b128 v[176:179], v144
	v_add3_u32 v144, v99, v182, s81
	ds_read_b128 v[180:183], v144
	ds_read_b128 v[184:187], v144 offset:2048
	ds_read_b128 v[206:209], v144 offset:4096
	ds_read_b128 v[216:219], v144 offset:6144
	s_waitcnt lgkmcnt(0)
	v_mfma_f32_16x16x32_bf16 v[60:63], v[146:149], v[180:183], v[60:63]
	v_mfma_f32_16x16x32_bf16 v[56:59], v[176:179], v[180:183], v[56:59]
	v_mfma_f32_16x16x32_bf16 v[52:55], v[146:149], v[184:187], v[52:55]
	v_mfma_f32_16x16x32_bf16 v[48:51], v[176:179], v[184:187], v[48:51]
	v_mfma_f32_16x16x32_bf16 v[44:47], v[146:149], v[206:209], v[44:47]
	v_mfma_f32_16x16x32_bf16 v[40:43], v[176:179], v[206:209], v[40:43]
	v_mfma_f32_16x16x32_bf16 v[36:39], v[146:149], v[216:219], v[36:39]
	v_mfma_f32_16x16x32_bf16 v[32:35], v[176:179], v[216:219], v[32:35]
	ds_read_b128 v[180:183], v144 offset:8192
	ds_read_b128 v[184:187], v144 offset:10240
	ds_read_b128 v[206:209], v144 offset:12288
	ds_read_b128 v[216:219], v144 offset:14336
	s_waitcnt lgkmcnt(0)
	v_mfma_f32_16x16x32_bf16 v[28:31], v[146:149], v[180:183], v[28:31]
	v_mfma_f32_16x16x32_bf16 v[24:27], v[176:179], v[180:183], v[24:27]
	v_mfma_f32_16x16x32_bf16 v[20:23], v[146:149], v[184:187], v[20:23]
	v_mfma_f32_16x16x32_bf16 v[16:19], v[176:179], v[184:187], v[16:19]
	v_mfma_f32_16x16x32_bf16 v[12:15], v[146:149], v[206:209], v[12:15]
	v_mfma_f32_16x16x32_bf16 v[8:11], v[176:179], v[206:209], v[8:11]
	v_mfma_f32_16x16x32_bf16 v[4:7], v[146:149], v[216:219], v[4:7]
	v_mfma_f32_16x16x32_bf16 v[0:3], v[176:179], v[216:219], v[0:3]
	v_add_u32_e32 v144, v151, v107
	v_or_b32_e32 v146, 0x18000, v144
	v_add3_u32 v99, v99, v107, s81
	v_add_u32_e32 v144, 0x18800, v144
	ds_read_b128 v[146:149], v146
	ds_read_b128 v[176:179], v144
	ds_read_b128 v[180:183], v99
	ds_read_b128 v[184:187], v99 offset:2048
	ds_read_b128 v[206:209], v99 offset:4096
	ds_read_b128 v[216:219], v99 offset:6144
	s_waitcnt lgkmcnt(0)
	v_mfma_f32_16x16x32_bf16 v[60:63], v[146:149], v[180:183], v[60:63]
	v_mfma_f32_16x16x32_bf16 v[56:59], v[176:179], v[180:183], v[56:59]
	v_mfma_f32_16x16x32_bf16 v[52:55], v[146:149], v[184:187], v[52:55]
	v_mfma_f32_16x16x32_bf16 v[48:51], v[176:179], v[184:187], v[48:51]
	v_mfma_f32_16x16x32_bf16 v[44:47], v[146:149], v[206:209], v[44:47]
	v_mfma_f32_16x16x32_bf16 v[40:43], v[176:179], v[206:209], v[40:43]
	v_mfma_f32_16x16x32_bf16 v[180:183], v[146:149], v[216:219], v[36:39]
	v_mfma_f32_16x16x32_bf16 v[32:35], v[176:179], v[216:219], v[32:35]
	s_nop 1
	ds_read_b128 v[36:39], v99 offset:8192
	ds_read_b128 v[184:187], v99 offset:10240
	ds_read_b128 v[206:209], v99 offset:12288
	ds_read_b128 v[216:219], v99 offset:14336
	s_waitcnt lgkmcnt(0)
	v_mfma_f32_16x16x32_bf16 v[28:31], v[146:149], v[36:39], v[28:31]
	v_mfma_f32_16x16x32_bf16 v[24:27], v[176:179], v[36:39], v[24:27]
	v_mfma_f32_16x16x32_bf16 v[20:23], v[146:149], v[184:187], v[20:23]
	v_mfma_f32_16x16x32_bf16 v[16:19], v[176:179], v[184:187], v[16:19]
	v_mfma_f32_16x16x32_bf16 v[12:15], v[146:149], v[206:209], v[12:15]
	v_mfma_f32_16x16x32_bf16 v[8:11], v[176:179], v[206:209], v[8:11]
	v_mfma_f32_16x16x32_bf16 v[4:7], v[146:149], v[216:219], v[4:7]
	v_mfma_f32_16x16x32_bf16 v[0:3], v[176:179], v[216:219], v[0:3]
	s_lshl_b32 s0, s69, 15
	v_lshl_add_u64 v[36:37], v[112:113], 0, s[0:1]
	v_lshl_add_u64 v[38:39], v[36:37], 0, v[118:119]
	global_load_dwordx2 v[216:217], v[38:39], off
	global_load_dwordx2 v[218:219], v[38:39], off offset:512
	v_lshl_add_u64 v[38:39], v[36:37], 0, v[120:121]
	global_load_dwordx2 v[220:221], v[38:39], off
	global_load_dwordx2 v[222:223], v[38:39], off offset:512
	v_lshl_add_u64 v[38:39], v[36:37], 0, v[126:127]
	global_load_dwordx2 v[224:225], v[38:39], off
	global_load_dwordx2 v[226:227], v[38:39], off offset:512
	v_lshl_add_u64 v[38:39], v[36:37], 0, v[128:129]
	global_load_dwordx2 v[228:229], v[38:39], off
	global_load_dwordx2 v[230:231], v[38:39], off offset:512
	v_lshl_add_u64 v[38:39], v[36:37], 0, v[134:135]
	global_load_dwordx2 v[232:233], v[38:39], off
	global_load_dwordx2 v[234:235], v[38:39], off offset:512
	v_lshl_add_u64 v[38:39], v[36:37], 0, v[136:137]
	global_load_dwordx2 v[236:237], v[38:39], off
	global_load_dwordx2 v[238:239], v[38:39], off offset:512
	v_lshl_add_u64 v[38:39], v[36:37], 0, v[142:143]
	global_load_dwordx2 v[240:241], v[38:39], off
	global_load_dwordx2 v[242:243], v[38:39], off offset:512
	v_lshl_add_u64 v[38:39], v[36:37], 0, v[154:155]
	global_load_dwordx2 v[244:245], v[38:39], off
	global_load_dwordx2 v[246:247], v[38:39], off offset:512
	s_add_i32 s69, s69, 1
	s_add_u32 s24, s24, 0x100000
	s_addc_u32 s25, s25, 0
	s_cmp_eq_u32 s69, 3
	s_waitcnt vmcnt(0)
	v_lshlrev_b32_e32 v146, 16, v216
	v_and_b32_e32 v147, 0xffff0000, v216
	v_pk_fma_f32 v[174:175], v[60:61], v[146:147], v[174:175]
	v_lshlrev_b32_e32 v148, 16, v219
	v_and_b32_e32 v149, 0xffff0000, v219
	v_pk_fma_f32 v[168:169], v[58:59], v[148:149], v[168:169]
	v_lshlrev_b32_e32 v146, 16, v218
	v_and_b32_e32 v147, 0xffff0000, v218
	v_pk_fma_f32 v[170:171], v[56:57], v[146:147], v[170:171]
	v_lshlrev_b32_e32 v148, 16, v217
	v_and_b32_e32 v149, 0xffff0000, v217
	v_pk_fma_f32 v[172:173], v[62:63], v[148:149], v[172:173]
	v_lshlrev_b32_e32 v146, 16, v220
	v_and_b32_e32 v147, 0xffff0000, v220
	v_pk_fma_f32 v[166:167], v[52:53], v[146:147], v[166:167]
	v_lshlrev_b32_e32 v148, 16, v223
	v_and_b32_e32 v149, 0xffff0000, v223
	v_pk_fma_f32 v[160:161], v[50:51], v[148:149], v[160:161]
	v_lshlrev_b32_e32 v146, 16, v222
	v_and_b32_e32 v147, 0xffff0000, v222
	v_pk_fma_f32 v[162:163], v[48:49], v[146:147], v[162:163]
	v_lshlrev_b32_e32 v148, 16, v221
	v_and_b32_e32 v149, 0xffff0000, v221
	v_pk_fma_f32 v[164:165], v[54:55], v[148:149], v[164:165]
	v_lshlrev_b32_e32 v146, 16, v224
	v_and_b32_e32 v147, 0xffff0000, v224
	v_pk_fma_f32 v[158:159], v[44:45], v[146:147], v[158:159]
	v_lshlrev_b32_e32 v148, 16, v227
	v_and_b32_e32 v149, 0xffff0000, v227
	v_pk_fma_f32 v[138:139], v[42:43], v[148:149], v[138:139]
	v_lshlrev_b32_e32 v146, 16, v226
	v_and_b32_e32 v147, 0xffff0000, v226
	v_pk_fma_f32 v[140:141], v[40:41], v[146:147], v[140:141]
	v_lshlrev_b32_e32 v148, 16, v225
	v_and_b32_e32 v149, 0xffff0000, v225
	v_pk_fma_f32 v[156:157], v[46:47], v[148:149], v[156:157]
	v_lshlrev_b32_e32 v146, 16, v229
	v_and_b32_e32 v147, 0xffff0000, v229
	v_pk_fma_f32 v[130:131], v[182:183], v[146:147], v[130:131]
	v_lshlrev_b32_e32 v148, 16, v230
	v_and_b32_e32 v149, 0xffff0000, v230
	v_pk_fma_f32 v[124:125], v[32:33], v[148:149], v[124:125]
	v_lshlrev_b32_e32 v146, 16, v231
	v_and_b32_e32 v147, 0xffff0000, v231
	v_pk_fma_f32 v[122:123], v[34:35], v[146:147], v[122:123]
	v_lshlrev_b32_e32 v148, 16, v228
	v_and_b32_e32 v149, 0xffff0000, v228
	v_pk_fma_f32 v[132:133], v[180:181], v[148:149], v[132:133]
	v_lshlrev_b32_e32 v146, 16, v232
	v_and_b32_e32 v147, 0xffff0000, v232
	v_pk_fma_f32 v[116:117], v[28:29], v[146:147], v[116:117]
	v_lshlrev_b32_e32 v148, 16, v233
	v_and_b32_e32 v149, 0xffff0000, v233
	v_pk_fma_f32 v[114:115], v[30:31], v[148:149], v[114:115]
	v_lshlrev_b32_e32 v146, 16, v234
	v_and_b32_e32 v147, 0xffff0000, v234
	v_pk_fma_f32 v[110:111], v[24:25], v[146:147], v[110:111]
	v_lshlrev_b32_e32 v148, 16, v235
	v_and_b32_e32 v149, 0xffff0000, v235
	v_pk_fma_f32 v[108:109], v[26:27], v[148:149], v[108:109]
	v_lshlrev_b32_e32 v146, 16, v236
	v_and_b32_e32 v147, 0xffff0000, v236
	v_pk_fma_f32 v[104:105], v[20:21], v[146:147], v[104:105]
	v_lshlrev_b32_e32 v148, 16, v237
	v_and_b32_e32 v149, 0xffff0000, v237
	v_pk_fma_f32 v[102:103], v[22:23], v[148:149], v[102:103]
	v_lshlrev_b32_e32 v146, 16, v238
	v_and_b32_e32 v147, 0xffff0000, v238
	v_pk_fma_f32 v[94:95], v[16:17], v[146:147], v[94:95]
	v_lshlrev_b32_e32 v148, 16, v239
	v_and_b32_e32 v149, 0xffff0000, v239
	v_pk_fma_f32 v[92:93], v[18:19], v[148:149], v[92:93]
	v_lshlrev_b32_e32 v146, 16, v240
	v_and_b32_e32 v147, 0xffff0000, v240
	v_pk_fma_f32 v[86:87], v[12:13], v[146:147], v[86:87]
	v_lshlrev_b32_e32 v148, 16, v241
	v_and_b32_e32 v149, 0xffff0000, v241
	v_pk_fma_f32 v[84:85], v[14:15], v[148:149], v[84:85]
	v_lshlrev_b32_e32 v146, 16, v242
	v_and_b32_e32 v147, 0xffff0000, v242
	v_pk_fma_f32 v[80:81], v[8:9], v[146:147], v[80:81]
	v_lshlrev_b32_e32 v148, 16, v243
	v_and_b32_e32 v149, 0xffff0000, v243
	v_pk_fma_f32 v[78:79], v[10:11], v[148:149], v[78:79]
	v_lshlrev_b32_e32 v146, 16, v244
	v_and_b32_e32 v147, 0xffff0000, v244
	v_pk_fma_f32 v[74:75], v[4:5], v[146:147], v[74:75]
	v_lshlrev_b32_e32 v148, 16, v245
	v_and_b32_e32 v149, 0xffff0000, v245
	v_pk_fma_f32 v[72:73], v[6:7], v[148:149], v[72:73]
	v_lshlrev_b32_e32 v146, 16, v247
	v_and_b32_e32 v147, 0xffff0000, v247
	v_pk_fma_f32 v[68:69], v[2:3], v[146:147], v[68:69]
	v_lshlrev_b32_e32 v148, 16, v246
	v_and_b32_e32 v149, 0xffff0000, v246
	v_pk_fma_f32 v[66:67], v[0:1], v[148:149], v[66:67]
	s_cbranch_scc1 .LBB0_271

.LBB0_423:
	s_mov_b32 s0, 0x18000
	v_add3_u32 v144, v138, v139, s0
	v_add3_u32 v139, v136, v139, s81
	ds_read_b128 v[128:131], v144
	ds_read_b128 v[132:135], v144 offset:2048
	ds_read_b128 v[140:143], v144 offset:4096
	ds_read_b128 v[146:149], v144 offset:6144
	ds_read_b128 v[154:157], v139
	ds_read_b128 v[158:161], v139 offset:2048
	ds_read_b128 v[162:165], v139 offset:4096
	ds_read_b128 v[166:169], v139 offset:6144
	ds_read_b128 v[170:173], v139 offset:8192
	ds_read_b128 v[174:177], v139 offset:10240
	ds_read_b128 v[178:181], v139 offset:12288
	ds_read_b128 v[182:185], v139 offset:14336
	s_waitcnt lgkmcnt(0)
	v_mfma_f32_16x16x32_bf16 v[124:127], v[128:131], v[154:157], v[124:127]
	v_mfma_f32_16x16x32_bf16 v[120:123], v[132:135], v[154:157], v[120:123]
	v_mfma_f32_16x16x32_bf16 v[116:119], v[140:143], v[154:157], v[116:119]
	v_mfma_f32_16x16x32_bf16 v[112:115], v[146:149], v[154:157], v[112:115]
	v_mfma_f32_16x16x32_bf16 v[108:111], v[128:131], v[158:161], v[108:111]
	v_mfma_f32_16x16x32_bf16 v[104:107], v[132:135], v[158:161], v[104:107]
	v_mfma_f32_16x16x32_bf16 v[100:103], v[140:143], v[158:161], v[100:103]
	v_mfma_f32_16x16x32_bf16 v[96:99], v[146:149], v[158:161], v[96:99]
	v_mfma_f32_16x16x32_bf16 v[92:95], v[128:131], v[162:165], v[92:95]
	v_mfma_f32_16x16x32_bf16 v[84:87], v[132:135], v[162:165], v[84:87]
	v_mfma_f32_16x16x32_bf16 v[80:83], v[140:143], v[162:165], v[80:83]
	v_mfma_f32_16x16x32_bf16 v[76:79], v[146:149], v[162:165], v[76:79]
	v_mfma_f32_16x16x32_bf16 v[72:75], v[128:131], v[166:169], v[72:75]
	v_mfma_f32_16x16x32_bf16 v[68:71], v[132:135], v[166:169], v[68:71]
	v_mfma_f32_16x16x32_bf16 v[64:67], v[140:143], v[166:169], v[64:67]
	v_mfma_f32_16x16x32_bf16 v[60:63], v[146:149], v[166:169], v[60:63]
	v_add3_u32 v138, v138, v137, s0
	v_add3_u32 v144, v136, v137, s81
	ds_read_b128 v[154:157], v138
	ds_read_b128 v[162:165], v138 offset:2048
	ds_read_b128 v[166:169], v138 offset:4096
	ds_read_b128 v[186:189], v138 offset:6144
	ds_read_b128 v[136:139], v144
	ds_read_b128 v[158:161], v144 offset:2048
	ds_read_b128 v[206:209], v144 offset:4096
	ds_read_b128 v[216:219], v144 offset:6144
	v_mfma_f32_16x16x32_bf16 v[56:59], v[128:131], v[170:173], v[56:59]
	v_mfma_f32_16x16x32_bf16 v[52:55], v[132:135], v[170:173], v[52:55]
	v_mfma_f32_16x16x32_bf16 v[48:51], v[140:143], v[170:173], v[48:51]
	v_mfma_f32_16x16x32_bf16 v[44:47], v[146:149], v[170:173], v[44:47]
	v_mfma_f32_16x16x32_bf16 v[40:43], v[128:131], v[174:177], v[40:43]
	v_mfma_f32_16x16x32_bf16 v[36:39], v[132:135], v[174:177], v[36:39]
	v_mfma_f32_16x16x32_bf16 v[32:35], v[140:143], v[174:177], v[32:35]
	v_mfma_f32_16x16x32_bf16 v[28:31], v[146:149], v[174:177], v[28:31]
	v_mfma_f32_16x16x32_bf16 v[24:27], v[128:131], v[178:181], v[24:27]
	v_mfma_f32_16x16x32_bf16 v[20:23], v[132:135], v[178:181], v[20:23]
	v_mfma_f32_16x16x32_bf16 v[16:19], v[140:143], v[178:181], v[16:19]
	v_mfma_f32_16x16x32_bf16 v[12:15], v[146:149], v[178:181], v[12:15]
	v_mfma_f32_16x16x32_bf16 v[8:11], v[128:131], v[182:185], v[8:11]
	v_mfma_f32_16x16x32_bf16 v[4:7], v[132:135], v[182:185], v[4:7]
	v_mfma_f32_16x16x32_bf16 v[128:131], v[140:143], v[182:185], v[0:3]
	v_mfma_f32_16x16x32_bf16 v[132:135], v[146:149], v[182:185], v[88:91]
	s_nop 1
	ds_read_b128 v[0:3], v144 offset:8192
	ds_read_b128 v[140:143], v144 offset:10240
	ds_read_b128 v[146:149], v144 offset:12288
	ds_read_b128 v[170:173], v144 offset:14336
	s_waitcnt lgkmcnt(0)
	v_mfma_f32_16x16x32_bf16 v[124:127], v[154:157], v[136:139], v[124:127]
	v_mfma_f32_16x16x32_bf16 v[120:123], v[162:165], v[136:139], v[120:123]
	v_mfma_f32_16x16x32_bf16 v[116:119], v[166:169], v[136:139], v[116:119]
	v_mfma_f32_16x16x32_bf16 v[112:115], v[186:189], v[136:139], v[112:115]
	v_mfma_f32_16x16x32_bf16 v[108:111], v[154:157], v[158:161], v[108:111]
	v_mfma_f32_16x16x32_bf16 v[104:107], v[162:165], v[158:161], v[104:107]
	v_mfma_f32_16x16x32_bf16 v[100:103], v[166:169], v[158:161], v[100:103]
	v_mfma_f32_16x16x32_bf16 v[96:99], v[186:189], v[158:161], v[96:99]
	v_mfma_f32_16x16x32_bf16 v[92:95], v[154:157], v[206:209], v[92:95]
	v_mfma_f32_16x16x32_bf16 v[88:91], v[162:165], v[206:209], v[84:87]
	v_mfma_f32_16x16x32_bf16 v[84:87], v[166:169], v[206:209], v[80:83]
	v_mfma_f32_16x16x32_bf16 v[80:83], v[186:189], v[206:209], v[76:79]
	v_mfma_f32_16x16x32_bf16 v[76:79], v[154:157], v[216:219], v[72:75]
	v_mfma_f32_16x16x32_bf16 v[72:75], v[162:165], v[216:219], v[68:71]
	v_mfma_f32_16x16x32_bf16 v[68:71], v[166:169], v[216:219], v[64:67]
	v_mfma_f32_16x16x32_bf16 v[64:67], v[186:189], v[216:219], v[60:63]
	v_mfma_f32_16x16x32_bf16 v[60:63], v[154:157], v[0:3], v[56:59]
	s_lshl_b32 s0, s24, 8
	s_movk_i32 s2, 0x27f
	s_lshl_b32 s26, s6, 8
	v_mfma_f32_16x16x32_bf16 v[56:59], v[162:165], v[0:3], v[52:55]
	s_mov_b64 s[20:21], s[74:75]
	v_mfma_f32_16x16x32_bf16 v[52:55], v[166:169], v[0:3], v[48:51]
	v_mfma_f32_16x16x32_bf16 v[48:51], v[186:189], v[0:3], v[44:47]
	v_mfma_f32_16x16x32_bf16 v[0:3], v[154:157], v[170:173], v[8:11]
	s_nop 2
	v_mov_b32_e32 v8, v190
	v_mfma_f32_16x16x32_bf16 v[44:47], v[154:157], v[140:143], v[40:43]
	v_mfma_f32_16x16x32_bf16 v[40:43], v[162:165], v[140:143], v[36:39]
	v_ashrrev_i32_e32 v160, 8, v8
	v_and_b32_e32 v159, 15, v8
	v_bfe_u32 v151, v8, 4, 2
	v_mfma_f32_16x16x32_bf16 v[36:39], v[166:169], v[140:143], v[32:35]
	v_mfma_f32_16x16x32_bf16 v[32:35], v[186:189], v[140:143], v[28:31]
	v_mfma_f32_16x16x32_bf16 v[28:31], v[154:157], v[146:149], v[24:27]
	v_mfma_f32_16x16x32_bf16 v[24:27], v[162:165], v[146:149], v[20:23]
	v_mfma_f32_16x16x32_bf16 v[20:23], v[166:169], v[146:149], v[16:19]
	v_mfma_f32_16x16x32_bf16 v[16:19], v[186:189], v[146:149], v[12:15]
	s_nop 2
	v_and_b32_e32 v12, 0xc0, v8
	v_mfma_f32_16x16x32_bf16 v[4:7], v[162:165], v[170:173], v[4:7]
	v_or_b32_e32 v154, s0, v12
	v_cmp_lt_i32_e32 vcc, s2, v154
	v_mfma_f32_16x16x32_bf16 v[8:11], v[166:169], v[170:173], v[128:131]
	v_mfma_f32_16x16x32_bf16 v[12:15], v[186:189], v[170:173], v[132:135]
	s_and_saveexec_b64 s[2:3], vcc
	s_xor_b64 s[22:23], exec, s[2:3]
	s_cbranch_execz .LBB0_456
	s_cmpk_gt_u32 s0, 0x2ff
	s_mov_b64 s[2:3], -1
	s_cbranch_scc0 .LBB0_454
	s_cmpk_lt_u32 s0, 0x500
	s_cselect_b64 s[24:25], -1, 0
	s_add_i32 s2, s0, 0xfffff700
	s_cmpk_lt_u32 s2, 0x200
	s_cselect_b64 s[2:3], -1, 0
	s_or_b64 s[2:3], s[24:25], s[2:3]
	s_andn2_b64 vcc, exec, s[2:3]
	s_mov_b64 s[2:3], -1
	s_cbranch_vccz .LBB0_451
	s_cmpk_gt_u32 s0, 0x6ff
	s_cbranch_scc0 .LBB0_432
	v_lshlrev_b32_e32 v128, 2, v151
	s_cmpk_gt_u32 s0, 0x8ff
	v_lshlrev_b32_e32 v144, 1, v128
	s_cbranch_scc0 .LBB0_429
	v_readlane_b32 s40, v255, 27
	v_readlane_b32 s54, v255, 41
	v_readlane_b32 s55, v255, 42
	s_mov_b64 s[2:3], s[54:55]
	s_mul_i32 s0, s77, 0x3000
	v_add_u32_e32 v146, 0xfffff500, v154
	s_add_u32 s2, s2, s0
	s_mul_hi_i32 s0, s77, 0x3000
	v_ashrrev_i32_e32 v147, 31, v146
	s_addc_u32 s3, s3, s0
	v_lshl_add_u64 v[130:131], v[146:147], 2, s[2:3]
	v_lshlrev_b32_e32 v128, 2, v128
	v_mov_b32_e32 v129, v145
	v_lshl_add_u64 v[128:129], v[130:131], 0, v[128:129]
	flat_load_dwordx4 v[140:143], v[128:129]
	flat_load_dwordx4 v[136:139], v[128:129] offset:64
	flat_load_dwordx4 v[132:135], v[128:129] offset:128
	s_nop 0
	flat_load_dwordx4 v[128:131], v[128:129] offset:192
	v_lshlrev_b32_e32 v149, 2, v159
	v_lshl_or_b32 v149, v160, 9, v149
	v_add_u32_e32 v158, 0x20800, v149
	ds_read_b32 v149, v158
	v_lshlrev_b64 v[146:147], 5, v[146:147]
	v_lshl_add_u64 v[146:147], v[146:147], 0, s[20:21]
	v_lshlrev_b32_e32 v144, 4, v144
	v_lshl_add_u32 v144, v159, 3, v144
	v_lshl_add_u64 v[146:147], v[146:147], 0, v[144:145]
	s_mov_b64 s[2:3], 0xb1e0000
	v_lshl_add_u64 v[156:157], v[146:147], 0, s[2:3]
	v_or_b32_e32 v148, s26, v159
	v_lshl_add_u32 v155, v160, 7, v148
	s_movk_i32 s0, 0x1800
	v_readlane_b32 s41, v255, 28
	v_readlane_b32 s42, v255, 29
	v_readlane_b32 s43, v255, 30
	v_readlane_b32 s44, v255, 31
	v_readlane_b32 s45, v255, 32
	v_readlane_b32 s46, v255, 33
	v_readlane_b32 s47, v255, 34
	v_readlane_b32 s48, v255, 35
	v_readlane_b32 s49, v255, 36
	v_readlane_b32 s50, v255, 37
	v_readlane_b32 s51, v255, 38
	v_readlane_b32 s52, v255, 39
	v_readlane_b32 s53, v255, 40
	s_waitcnt vmcnt(0) lgkmcnt(0)
	v_fma_f32 v146, v124, v149, v140
	v_fma_f32 v147, v120, v149, v136
	v_mul_f32_e32 v147, 0xbfb8aa3b, v147
	v_mul_f32_e32 v146, 0xbfb8aa3b, v146
	v_exp_f32_e32 v147, v147
	v_exp_f32_e32 v146, v146
	v_fma_f32 v148, v116, v149, v132
	v_fma_f32 v162, v125, v149, v141
	v_fma_f32 v163, v121, v149, v137
	v_fma_f32 v164, v117, v149, v133
	v_fma_f32 v165, v113, v149, v129
	v_fma_f32 v166, v126, v149, v142
	v_fma_f32 v167, v122, v149, v138
	v_fma_f32 v168, v118, v149, v134
	v_fma_f32 v169, v114, v149, v130
	v_fma_f32 v170, v127, v149, v143
	v_fma_f32 v171, v123, v149, v139
	v_fma_f32 v172, v119, v149, v135
	v_add_f32_e32 v147, 1.0, v147
	v_mul_f32_e32 v148, 0xbfb8aa3b, v148
	v_mul_f32_e32 v162, 0xbfb8aa3b, v162
	v_mul_f32_e32 v163, 0xbfb8aa3b, v163
	v_mul_f32_e32 v164, 0xbfb8aa3b, v164
	v_mul_f32_e32 v165, 0xbfb8aa3b, v165
	v_mul_f32_e32 v166, 0xbfb8aa3b, v166
	v_mul_f32_e32 v167, 0xbfb8aa3b, v167
	v_mul_f32_e32 v168, 0xbfb8aa3b, v168
	v_mul_f32_e32 v169, 0xbfb8aa3b, v169
	v_mul_f32_e32 v170, 0xbfb8aa3b, v170
	v_mul_f32_e32 v171, 0xbfb8aa3b, v171
	v_mul_f32_e32 v172, 0xbfb8aa3b, v172
	v_add_f32_e32 v146, 1.0, v146
	v_rcp_f32_e32 v174, v147
	v_fma_f32 v147, v115, v149, v131
	v_exp_f32_e32 v148, v148
	v_exp_f32_e32 v162, v162
	v_exp_f32_e32 v163, v163
	v_exp_f32_e32 v164, v164
	v_exp_f32_e32 v165, v165
	v_exp_f32_e32 v166, v166
	v_exp_f32_e32 v167, v167
	v_exp_f32_e32 v168, v168
	v_exp_f32_e32 v169, v169
	v_exp_f32_e32 v170, v170
	v_exp_f32_e32 v171, v171
	v_rcp_f32_e32 v173, v146
	v_exp_f32_e32 v146, v172
	v_mul_f32_e32 v147, 0xbfb8aa3b, v147
	v_exp_f32_e32 v147, v147
	v_fma_f32 v161, v112, v149, v128
	v_mul_f32_e32 v161, 0xbfb8aa3b, v161
	v_exp_f32_e32 v161, v161
	v_add_f32_e32 v148, 1.0, v148
	v_add_f32_e32 v162, 1.0, v162
	v_add_f32_e32 v163, 1.0, v163
	v_add_f32_e32 v164, 1.0, v164
	v_add_f32_e32 v165, 1.0, v165
	v_add_f32_e32 v166, 1.0, v166
	v_add_f32_e32 v167, 1.0, v167
	v_add_f32_e32 v168, 1.0, v168
	v_add_f32_e32 v169, 1.0, v169
	v_add_f32_e32 v170, 1.0, v170
	v_add_f32_e32 v171, 1.0, v171
	v_add_f32_e32 v146, 1.0, v146
	v_rcp_f32_e32 v175, v148
	v_rcp_f32_e32 v148, v162
	v_rcp_f32_e32 v162, v163
	v_rcp_f32_e32 v163, v164
	v_rcp_f32_e32 v164, v165
	v_rcp_f32_e32 v165, v166
	v_rcp_f32_e32 v166, v167
	v_rcp_f32_e32 v167, v168
	v_rcp_f32_e32 v168, v169
	v_rcp_f32_e32 v169, v170
	v_rcp_f32_e32 v170, v171
	v_rcp_f32_e32 v171, v146
	v_add_f32_e32 v146, 1.0, v147
	v_rcp_f32_e32 v172, v146
	v_and_b32_e32 v146, 0xfffffff0, v155
	v_mad_i64_i32 v[146:147], s[2:3], v146, s0, v[156:157]
	v_cvt_pk_bf16_f32 v148, v173, v148
	v_cvt_pk_bf16_f32 v149, v165, v169
	flat_store_dwordx2 v[146:147], v[148:149]
	v_cvt_pk_bf16_f32 v148, v174, v162
	v_cvt_pk_bf16_f32 v149, v166, v170
	v_add_f32_e32 v161, 1.0, v161
	flat_store_dwordx2 v[146:147], v[148:149] offset:512
	v_cvt_pk_bf16_f32 v148, v175, v163
	v_cvt_pk_bf16_f32 v149, v167, v171
	v_rcp_f32_e32 v161, v161
	flat_store_dwordx2 v[146:147], v[148:149] offset:1024
	v_cvt_pk_bf16_f32 v148, v161, v164
	v_cvt_pk_bf16_f32 v149, v168, v172
	flat_store_dwordx2 v[146:147], v[148:149] offset:1536
	ds_read_b32 v146, v158 offset:64
	v_or_b32_e32 v149, 16, v155
	s_waitcnt lgkmcnt(0)
	v_fma_f32 v147, v108, v146, v140
	v_mul_f32_e32 v147, 0xbfb8aa3b, v147
	v_fma_f32 v148, v104, v146, v136
	v_exp_f32_e32 v147, v147
	v_mul_f32_e32 v148, 0xbfb8aa3b, v148
	v_exp_f32_e32 v148, v148
	v_fma_f32 v162, v96, v146, v128
	v_add_f32_e32 v147, 1.0, v147
	v_rcp_f32_e32 v161, v147
	v_add_f32_e32 v147, 1.0, v148
	v_fma_f32 v148, v100, v146, v132
	v_mul_f32_e32 v148, 0xbfb8aa3b, v148
	v_exp_f32_e32 v148, v148
	v_mul_f32_e32 v162, 0xbfb8aa3b, v162
	v_exp_f32_e32 v162, v162
	v_rcp_f32_e32 v163, v147
	v_add_f32_e32 v147, 1.0, v148
	v_fma_f32 v148, v109, v146, v141
	v_rcp_f32_e32 v164, v147
	v_add_f32_e32 v147, 1.0, v162
	v_mul_f32_e32 v148, 0xbfb8aa3b, v148
	v_fma_f32 v162, v105, v146, v137
	v_exp_f32_e32 v148, v148
	v_mul_f32_e32 v162, 0xbfb8aa3b, v162
	v_exp_f32_e32 v162, v162
	v_rcp_f32_e32 v165, v147
	v_add_f32_e32 v147, 1.0, v148
	v_rcp_f32_e32 v148, v147
	v_add_f32_e32 v147, 1.0, v162
	v_fma_f32 v162, v101, v146, v133
	v_mul_f32_e32 v162, 0xbfb8aa3b, v162
	v_fma_f32 v166, v97, v146, v129
	v_exp_f32_e32 v162, v162
	v_mul_f32_e32 v166, 0xbfb8aa3b, v166
	v_exp_f32_e32 v166, v166
	v_rcp_f32_e32 v167, v147
	v_add_f32_e32 v147, 1.0, v162
	v_rcp_f32_e32 v162, v147
	v_add_f32_e32 v147, 1.0, v166
	v_fma_f32 v166, v110, v146, v142
	v_mul_f32_e32 v166, 0xbfb8aa3b, v166
	v_fma_f32 v168, v106, v146, v138
	v_exp_f32_e32 v166, v166
	v_mul_f32_e32 v168, 0xbfb8aa3b, v168
	v_exp_f32_e32 v168, v168
	v_rcp_f32_e32 v169, v147
	v_add_f32_e32 v147, 1.0, v166
	v_rcp_f32_e32 v166, v147
	v_add_f32_e32 v147, 1.0, v168
	v_fma_f32 v168, v102, v146, v134
	v_mul_f32_e32 v168, 0xbfb8aa3b, v168
	v_fma_f32 v170, v98, v146, v130
	v_exp_f32_e32 v168, v168
	v_mul_f32_e32 v170, 0xbfb8aa3b, v170
	v_exp_f32_e32 v170, v170
	v_rcp_f32_e32 v171, v147
	v_add_f32_e32 v147, 1.0, v168
	v_rcp_f32_e32 v168, v147
	v_add_f32_e32 v147, 1.0, v170
	v_fma_f32 v170, v111, v146, v143
	v_mul_f32_e32 v170, 0xbfb8aa3b, v170
	v_fma_f32 v172, v107, v146, v139
	v_exp_f32_e32 v170, v170
	v_mul_f32_e32 v172, 0xbfb8aa3b, v172
	v_exp_f32_e32 v172, v172
	v_rcp_f32_e32 v173, v147
	v_add_f32_e32 v147, 1.0, v170
	v_rcp_f32_e32 v170, v147
	v_add_f32_e32 v147, 1.0, v172
	v_fma_f32 v172, v103, v146, v135
	v_fma_f32 v146, v99, v146, v131
	v_mul_f32_e32 v172, 0xbfb8aa3b, v172
	v_mul_f32_e32 v146, 0xbfb8aa3b, v146
	v_exp_f32_e32 v172, v172
	v_exp_f32_e32 v146, v146
	v_rcp_f32_e32 v174, v147
	v_cvt_pk_bf16_f32 v148, v161, v148
	v_add_f32_e32 v147, 1.0, v172
	v_add_f32_e32 v146, 1.0, v146
	v_rcp_f32_e32 v172, v147
	v_rcp_f32_e32 v175, v146
	v_and_b32_e32 v146, 0xfffffff0, v149
	v_mad_i64_i32 v[146:147], s[2:3], v146, s0, v[156:157]
	v_cvt_pk_bf16_f32 v149, v166, v170
	flat_store_dwordx2 v[146:147], v[148:149]
	v_cvt_pk_bf16_f32 v148, v163, v167
	v_cvt_pk_bf16_f32 v149, v171, v174
	flat_store_dwordx2 v[146:147], v[148:149] offset:512
	v_cvt_pk_bf16_f32 v148, v164, v162
	v_cvt_pk_bf16_f32 v149, v168, v172
	flat_store_dwordx2 v[146:147], v[148:149] offset:1024
	v_cvt_pk_bf16_f32 v148, v165, v169
	v_cvt_pk_bf16_f32 v149, v173, v175
	flat_store_dwordx2 v[146:147], v[148:149] offset:1536
	ds_read_b32 v146, v158 offset:128
	v_or_b32_e32 v149, 32, v155
	s_waitcnt lgkmcnt(0)
	v_fma_f32 v147, v92, v146, v140
	v_mul_f32_e32 v147, 0xbfb8aa3b, v147
	v_fma_f32 v148, v88, v146, v136
	v_exp_f32_e32 v147, v147
	v_mul_f32_e32 v148, 0xbfb8aa3b, v148
	v_exp_f32_e32 v148, v148
	v_fma_f32 v162, v80, v146, v128
	v_add_f32_e32 v147, 1.0, v147
	v_rcp_f32_e32 v161, v147
	v_add_f32_e32 v147, 1.0, v148
	v_fma_f32 v148, v84, v146, v132
	v_mul_f32_e32 v148, 0xbfb8aa3b, v148
	v_exp_f32_e32 v148, v148
	v_mul_f32_e32 v162, 0xbfb8aa3b, v162
	v_exp_f32_e32 v162, v162
	v_rcp_f32_e32 v163, v147
	v_add_f32_e32 v147, 1.0, v148
	v_fma_f32 v148, v93, v146, v141
	v_rcp_f32_e32 v164, v147
	v_add_f32_e32 v147, 1.0, v162
	v_mul_f32_e32 v148, 0xbfb8aa3b, v148
	v_fma_f32 v162, v89, v146, v137
	v_exp_f32_e32 v148, v148
	v_mul_f32_e32 v162, 0xbfb8aa3b, v162
	v_exp_f32_e32 v162, v162
	v_rcp_f32_e32 v165, v147
	v_add_f32_e32 v147, 1.0, v148
	v_rcp_f32_e32 v148, v147
	v_add_f32_e32 v147, 1.0, v162
	v_fma_f32 v162, v85, v146, v133
	v_mul_f32_e32 v162, 0xbfb8aa3b, v162
	v_fma_f32 v166, v81, v146, v129
	v_exp_f32_e32 v162, v162
	v_mul_f32_e32 v166, 0xbfb8aa3b, v166
	v_exp_f32_e32 v166, v166
	v_rcp_f32_e32 v167, v147
	v_add_f32_e32 v147, 1.0, v162
	v_rcp_f32_e32 v162, v147
	v_add_f32_e32 v147, 1.0, v166
	v_fma_f32 v166, v94, v146, v142
	v_mul_f32_e32 v166, 0xbfb8aa3b, v166
	v_fma_f32 v168, v90, v146, v138
	v_exp_f32_e32 v166, v166
	v_mul_f32_e32 v168, 0xbfb8aa3b, v168
	v_exp_f32_e32 v168, v168
	v_rcp_f32_e32 v169, v147
	v_add_f32_e32 v147, 1.0, v166
	v_rcp_f32_e32 v166, v147
	v_add_f32_e32 v147, 1.0, v168
	v_fma_f32 v168, v86, v146, v134
	v_mul_f32_e32 v168, 0xbfb8aa3b, v168
	v_fma_f32 v170, v82, v146, v130
	v_exp_f32_e32 v168, v168
	v_mul_f32_e32 v170, 0xbfb8aa3b, v170
	v_exp_f32_e32 v170, v170
	v_rcp_f32_e32 v171, v147
	v_add_f32_e32 v147, 1.0, v168
	v_rcp_f32_e32 v168, v147
	v_add_f32_e32 v147, 1.0, v170
	v_fma_f32 v170, v95, v146, v143
	v_mul_f32_e32 v170, 0xbfb8aa3b, v170
	v_fma_f32 v172, v91, v146, v139
	v_exp_f32_e32 v170, v170
	v_mul_f32_e32 v172, 0xbfb8aa3b, v172
	v_exp_f32_e32 v172, v172
	v_rcp_f32_e32 v173, v147
	v_add_f32_e32 v147, 1.0, v170
	v_rcp_f32_e32 v170, v147
	v_add_f32_e32 v147, 1.0, v172
	v_fma_f32 v172, v87, v146, v135
	v_fma_f32 v146, v83, v146, v131
	v_mul_f32_e32 v172, 0xbfb8aa3b, v172
	v_mul_f32_e32 v146, 0xbfb8aa3b, v146
	v_exp_f32_e32 v172, v172
	v_exp_f32_e32 v146, v146
	v_rcp_f32_e32 v174, v147
	v_cvt_pk_bf16_f32 v148, v161, v148
	v_add_f32_e32 v147, 1.0, v172
	v_add_f32_e32 v146, 1.0, v146
	v_rcp_f32_e32 v172, v147
	v_rcp_f32_e32 v175, v146
	v_and_b32_e32 v146, 0xfffffff0, v149
	v_mad_i64_i32 v[146:147], s[2:3], v146, s0, v[156:157]
	v_cvt_pk_bf16_f32 v149, v166, v170
	flat_store_dwordx2 v[146:147], v[148:149]
	v_cvt_pk_bf16_f32 v148, v163, v167
	v_cvt_pk_bf16_f32 v149, v171, v174
	flat_store_dwordx2 v[146:147], v[148:149] offset:512
	v_cvt_pk_bf16_f32 v148, v164, v162
	v_cvt_pk_bf16_f32 v149, v168, v172
	flat_store_dwordx2 v[146:147], v[148:149] offset:1024
	v_cvt_pk_bf16_f32 v148, v165, v169
	v_cvt_pk_bf16_f32 v149, v173, v175
	flat_store_dwordx2 v[146:147], v[148:149] offset:1536
	ds_read_b32 v146, v158 offset:192
	v_or_b32_e32 v149, 48, v155
	s_waitcnt lgkmcnt(0)
	v_fma_f32 v147, v76, v146, v140
	v_mul_f32_e32 v147, 0xbfb8aa3b, v147
	v_fma_f32 v148, v72, v146, v136
	v_exp_f32_e32 v147, v147
	v_mul_f32_e32 v148, 0xbfb8aa3b, v148
	v_exp_f32_e32 v148, v148
	v_fma_f32 v162, v64, v146, v128
	v_add_f32_e32 v147, 1.0, v147
	v_rcp_f32_e32 v161, v147
	v_add_f32_e32 v147, 1.0, v148
	v_fma_f32 v148, v68, v146, v132
	v_mul_f32_e32 v148, 0xbfb8aa3b, v148
	v_exp_f32_e32 v148, v148
	v_mul_f32_e32 v162, 0xbfb8aa3b, v162
	v_exp_f32_e32 v162, v162
	v_rcp_f32_e32 v163, v147
	v_add_f32_e32 v147, 1.0, v148
	v_fma_f32 v148, v77, v146, v141
	v_rcp_f32_e32 v164, v147
	v_add_f32_e32 v147, 1.0, v162
	v_mul_f32_e32 v148, 0xbfb8aa3b, v148
	v_fma_f32 v162, v73, v146, v137
	v_exp_f32_e32 v148, v148
	v_mul_f32_e32 v162, 0xbfb8aa3b, v162
	v_exp_f32_e32 v162, v162
	v_rcp_f32_e32 v165, v147
	v_add_f32_e32 v147, 1.0, v148
	v_rcp_f32_e32 v148, v147
	v_add_f32_e32 v147, 1.0, v162
	v_fma_f32 v162, v69, v146, v133
	v_mul_f32_e32 v162, 0xbfb8aa3b, v162
	v_fma_f32 v166, v65, v146, v129
	v_exp_f32_e32 v162, v162
	v_mul_f32_e32 v166, 0xbfb8aa3b, v166
	v_exp_f32_e32 v166, v166
	v_rcp_f32_e32 v167, v147
	v_add_f32_e32 v147, 1.0, v162
	v_rcp_f32_e32 v162, v147
	v_add_f32_e32 v147, 1.0, v166
	v_fma_f32 v166, v78, v146, v142
	v_mul_f32_e32 v166, 0xbfb8aa3b, v166
	v_fma_f32 v168, v74, v146, v138
	v_exp_f32_e32 v166, v166
	v_mul_f32_e32 v168, 0xbfb8aa3b, v168
	v_exp_f32_e32 v168, v168
	v_rcp_f32_e32 v169, v147
	v_add_f32_e32 v147, 1.0, v166
	v_rcp_f32_e32 v166, v147
	v_add_f32_e32 v147, 1.0, v168
	v_fma_f32 v168, v70, v146, v134
	v_mul_f32_e32 v168, 0xbfb8aa3b, v168
	v_fma_f32 v170, v66, v146, v130
	v_exp_f32_e32 v168, v168
	v_mul_f32_e32 v170, 0xbfb8aa3b, v170
	v_exp_f32_e32 v170, v170
	v_rcp_f32_e32 v171, v147
	v_add_f32_e32 v147, 1.0, v168
	v_rcp_f32_e32 v168, v147
	v_add_f32_e32 v147, 1.0, v170
	v_fma_f32 v170, v79, v146, v143
	v_mul_f32_e32 v170, 0xbfb8aa3b, v170
	v_fma_f32 v172, v75, v146, v139
	v_exp_f32_e32 v170, v170
	v_mul_f32_e32 v172, 0xbfb8aa3b, v172
	v_exp_f32_e32 v172, v172
	v_rcp_f32_e32 v173, v147
	v_add_f32_e32 v147, 1.0, v170
	v_rcp_f32_e32 v170, v147
	v_add_f32_e32 v147, 1.0, v172
	v_fma_f32 v172, v71, v146, v135
	v_fma_f32 v146, v67, v146, v131
	v_mul_f32_e32 v172, 0xbfb8aa3b, v172
	v_mul_f32_e32 v146, 0xbfb8aa3b, v146
	v_exp_f32_e32 v172, v172
	v_exp_f32_e32 v146, v146
	v_rcp_f32_e32 v174, v147
	v_cvt_pk_bf16_f32 v148, v161, v148
	v_add_f32_e32 v147, 1.0, v172
	v_add_f32_e32 v146, 1.0, v146
	v_rcp_f32_e32 v172, v147
	v_rcp_f32_e32 v175, v146
	v_and_b32_e32 v146, 0xfffffff0, v149
	v_mad_i64_i32 v[146:147], s[2:3], v146, s0, v[156:157]
	v_cvt_pk_bf16_f32 v149, v166, v170
	flat_store_dwordx2 v[146:147], v[148:149]
	v_cvt_pk_bf16_f32 v148, v163, v167
	v_cvt_pk_bf16_f32 v149, v171, v174
	flat_store_dwordx2 v[146:147], v[148:149] offset:512
	v_cvt_pk_bf16_f32 v148, v164, v162
	v_cvt_pk_bf16_f32 v149, v168, v172
	flat_store_dwordx2 v[146:147], v[148:149] offset:1024
	v_cvt_pk_bf16_f32 v148, v165, v169
	v_cvt_pk_bf16_f32 v149, v173, v175
	flat_store_dwordx2 v[146:147], v[148:149] offset:1536
	ds_read_b32 v146, v158 offset:256
	v_or_b32_e32 v149, 64, v155
	s_waitcnt lgkmcnt(0)
	v_fma_f32 v147, v60, v146, v140
	v_mul_f32_e32 v147, 0xbfb8aa3b, v147
	v_fma_f32 v148, v56, v146, v136
	v_exp_f32_e32 v147, v147
	v_mul_f32_e32 v148, 0xbfb8aa3b, v148
	v_exp_f32_e32 v148, v148
	v_fma_f32 v162, v48, v146, v128
	v_add_f32_e32 v147, 1.0, v147
	v_rcp_f32_e32 v161, v147
	v_add_f32_e32 v147, 1.0, v148
	v_fma_f32 v148, v52, v146, v132
	v_mul_f32_e32 v148, 0xbfb8aa3b, v148
	v_exp_f32_e32 v148, v148
	v_mul_f32_e32 v162, 0xbfb8aa3b, v162
	v_exp_f32_e32 v162, v162
	v_rcp_f32_e32 v163, v147
	v_add_f32_e32 v147, 1.0, v148
	v_fma_f32 v148, v61, v146, v141
	v_rcp_f32_e32 v164, v147
	v_add_f32_e32 v147, 1.0, v162
	v_mul_f32_e32 v148, 0xbfb8aa3b, v148
	v_fma_f32 v162, v57, v146, v137
	v_exp_f32_e32 v148, v148
	v_mul_f32_e32 v162, 0xbfb8aa3b, v162
	v_exp_f32_e32 v162, v162
	v_rcp_f32_e32 v165, v147
	v_add_f32_e32 v147, 1.0, v148
	v_rcp_f32_e32 v148, v147
	v_add_f32_e32 v147, 1.0, v162
	v_fma_f32 v162, v53, v146, v133
	v_mul_f32_e32 v162, 0xbfb8aa3b, v162
	v_fma_f32 v166, v49, v146, v129
	v_exp_f32_e32 v162, v162
	v_mul_f32_e32 v166, 0xbfb8aa3b, v166
	v_exp_f32_e32 v166, v166
	v_rcp_f32_e32 v167, v147
	v_add_f32_e32 v147, 1.0, v162
	v_rcp_f32_e32 v162, v147
	v_add_f32_e32 v147, 1.0, v166
	v_fma_f32 v166, v62, v146, v142
	v_mul_f32_e32 v166, 0xbfb8aa3b, v166
	v_fma_f32 v168, v58, v146, v138
	v_exp_f32_e32 v166, v166
	v_mul_f32_e32 v168, 0xbfb8aa3b, v168
	v_exp_f32_e32 v168, v168
	v_rcp_f32_e32 v169, v147
	v_add_f32_e32 v147, 1.0, v166
	v_rcp_f32_e32 v166, v147
	v_add_f32_e32 v147, 1.0, v168
	v_fma_f32 v168, v54, v146, v134
	v_mul_f32_e32 v168, 0xbfb8aa3b, v168
	v_fma_f32 v170, v50, v146, v130
	v_exp_f32_e32 v168, v168
	v_mul_f32_e32 v170, 0xbfb8aa3b, v170
	v_exp_f32_e32 v170, v170
	v_rcp_f32_e32 v171, v147
	v_add_f32_e32 v147, 1.0, v168
	v_rcp_f32_e32 v168, v147
	v_add_f32_e32 v147, 1.0, v170
	v_fma_f32 v170, v63, v146, v143
	v_mul_f32_e32 v170, 0xbfb8aa3b, v170
	v_fma_f32 v172, v59, v146, v139
	v_exp_f32_e32 v170, v170
	v_mul_f32_e32 v172, 0xbfb8aa3b, v172
	v_exp_f32_e32 v172, v172
	v_rcp_f32_e32 v173, v147
	v_add_f32_e32 v147, 1.0, v170
	v_rcp_f32_e32 v170, v147
	v_add_f32_e32 v147, 1.0, v172
	v_fma_f32 v172, v55, v146, v135
	v_fma_f32 v146, v51, v146, v131
	v_mul_f32_e32 v172, 0xbfb8aa3b, v172
	v_mul_f32_e32 v146, 0xbfb8aa3b, v146
	v_exp_f32_e32 v172, v172
	v_exp_f32_e32 v146, v146
	v_rcp_f32_e32 v174, v147
	v_cvt_pk_bf16_f32 v148, v161, v148
	v_add_f32_e32 v147, 1.0, v172
	v_add_f32_e32 v146, 1.0, v146
	v_rcp_f32_e32 v172, v147
	v_rcp_f32_e32 v175, v146
	v_and_b32_e32 v146, 0xfffffff0, v149
	v_mad_i64_i32 v[146:147], s[2:3], v146, s0, v[156:157]
	v_cvt_pk_bf16_f32 v149, v166, v170
	flat_store_dwordx2 v[146:147], v[148:149]
	v_cvt_pk_bf16_f32 v148, v163, v167
	v_cvt_pk_bf16_f32 v149, v171, v174
	flat_store_dwordx2 v[146:147], v[148:149] offset:512
	v_cvt_pk_bf16_f32 v148, v164, v162
	v_cvt_pk_bf16_f32 v149, v168, v172
	flat_store_dwordx2 v[146:147], v[148:149] offset:1024
	v_cvt_pk_bf16_f32 v148, v165, v169
	v_cvt_pk_bf16_f32 v149, v173, v175
	flat_store_dwordx2 v[146:147], v[148:149] offset:1536
	ds_read_b32 v146, v158 offset:320
	v_or_b32_e32 v149, 0x50, v155
	s_waitcnt lgkmcnt(0)
	v_fma_f32 v147, v44, v146, v140
	v_mul_f32_e32 v147, 0xbfb8aa3b, v147
	v_fma_f32 v148, v40, v146, v136
	v_exp_f32_e32 v147, v147
	v_mul_f32_e32 v148, 0xbfb8aa3b, v148
	v_exp_f32_e32 v148, v148
	v_fma_f32 v162, v32, v146, v128
	v_add_f32_e32 v147, 1.0, v147
	v_rcp_f32_e32 v161, v147
	v_add_f32_e32 v147, 1.0, v148
	v_fma_f32 v148, v36, v146, v132
	v_mul_f32_e32 v148, 0xbfb8aa3b, v148
	v_exp_f32_e32 v148, v148
	v_mul_f32_e32 v162, 0xbfb8aa3b, v162
	v_exp_f32_e32 v162, v162
	v_rcp_f32_e32 v163, v147
	v_add_f32_e32 v147, 1.0, v148
	v_fma_f32 v148, v45, v146, v141
	v_rcp_f32_e32 v164, v147
	v_add_f32_e32 v147, 1.0, v162
	v_mul_f32_e32 v148, 0xbfb8aa3b, v148
	v_fma_f32 v162, v41, v146, v137
	v_exp_f32_e32 v148, v148
	v_mul_f32_e32 v162, 0xbfb8aa3b, v162
	v_exp_f32_e32 v162, v162
	v_rcp_f32_e32 v165, v147
	v_add_f32_e32 v147, 1.0, v148
	v_rcp_f32_e32 v148, v147
	v_add_f32_e32 v147, 1.0, v162
	v_fma_f32 v162, v37, v146, v133
	v_mul_f32_e32 v162, 0xbfb8aa3b, v162
	v_fma_f32 v166, v33, v146, v129
	v_exp_f32_e32 v162, v162
	v_mul_f32_e32 v166, 0xbfb8aa3b, v166
	v_exp_f32_e32 v166, v166
	v_rcp_f32_e32 v167, v147
	v_add_f32_e32 v147, 1.0, v162
	v_rcp_f32_e32 v162, v147
	v_add_f32_e32 v147, 1.0, v166
	v_fma_f32 v166, v46, v146, v142
	v_mul_f32_e32 v166, 0xbfb8aa3b, v166
	v_fma_f32 v168, v42, v146, v138
	v_exp_f32_e32 v166, v166
	v_mul_f32_e32 v168, 0xbfb8aa3b, v168
	v_exp_f32_e32 v168, v168
	v_rcp_f32_e32 v169, v147
	v_add_f32_e32 v147, 1.0, v166
	v_rcp_f32_e32 v166, v147
	v_add_f32_e32 v147, 1.0, v168
	v_fma_f32 v168, v38, v146, v134
	v_mul_f32_e32 v168, 0xbfb8aa3b, v168
	v_fma_f32 v170, v34, v146, v130
	v_exp_f32_e32 v168, v168
	v_mul_f32_e32 v170, 0xbfb8aa3b, v170
	v_exp_f32_e32 v170, v170
	v_rcp_f32_e32 v171, v147
	v_add_f32_e32 v147, 1.0, v168
	v_rcp_f32_e32 v168, v147
	v_add_f32_e32 v147, 1.0, v170
	v_fma_f32 v170, v47, v146, v143
	v_mul_f32_e32 v170, 0xbfb8aa3b, v170
	v_fma_f32 v172, v43, v146, v139
	v_exp_f32_e32 v170, v170
	v_mul_f32_e32 v172, 0xbfb8aa3b, v172
	v_exp_f32_e32 v172, v172
	v_rcp_f32_e32 v173, v147
	v_add_f32_e32 v147, 1.0, v170
	v_rcp_f32_e32 v170, v147
	v_add_f32_e32 v147, 1.0, v172
	v_fma_f32 v172, v39, v146, v135
	v_fma_f32 v146, v35, v146, v131
	v_mul_f32_e32 v172, 0xbfb8aa3b, v172
	v_mul_f32_e32 v146, 0xbfb8aa3b, v146
	v_exp_f32_e32 v172, v172
	v_exp_f32_e32 v146, v146
	v_rcp_f32_e32 v174, v147
	v_cvt_pk_bf16_f32 v148, v161, v148
	v_add_f32_e32 v147, 1.0, v172
	v_add_f32_e32 v146, 1.0, v146
	v_rcp_f32_e32 v172, v147
	v_rcp_f32_e32 v175, v146
	v_and_b32_e32 v146, 0xfffffff0, v149
	v_mad_i64_i32 v[146:147], s[2:3], v146, s0, v[156:157]
	v_cvt_pk_bf16_f32 v149, v166, v170
	flat_store_dwordx2 v[146:147], v[148:149]
	v_cvt_pk_bf16_f32 v148, v163, v167
	v_cvt_pk_bf16_f32 v149, v171, v174
	flat_store_dwordx2 v[146:147], v[148:149] offset:512
	v_cvt_pk_bf16_f32 v148, v164, v162
	v_cvt_pk_bf16_f32 v149, v168, v172
	flat_store_dwordx2 v[146:147], v[148:149] offset:1024
	v_cvt_pk_bf16_f32 v148, v165, v169
	v_cvt_pk_bf16_f32 v149, v173, v175
	flat_store_dwordx2 v[146:147], v[148:149] offset:1536
	ds_read_b32 v146, v158 offset:384
	v_or_b32_e32 v149, 0x60, v155
	s_waitcnt lgkmcnt(0)
	v_fma_f32 v147, v28, v146, v140
	v_mul_f32_e32 v147, 0xbfb8aa3b, v147
	v_fma_f32 v148, v24, v146, v136
	v_exp_f32_e32 v147, v147
	v_mul_f32_e32 v148, 0xbfb8aa3b, v148
	v_exp_f32_e32 v148, v148
	v_fma_f32 v162, v16, v146, v128
	v_add_f32_e32 v147, 1.0, v147
	v_rcp_f32_e32 v161, v147
	v_add_f32_e32 v147, 1.0, v148
	v_fma_f32 v148, v20, v146, v132
	v_mul_f32_e32 v148, 0xbfb8aa3b, v148
	v_exp_f32_e32 v148, v148
	v_mul_f32_e32 v162, 0xbfb8aa3b, v162
	v_exp_f32_e32 v162, v162
	v_rcp_f32_e32 v163, v147
	v_add_f32_e32 v147, 1.0, v148
	v_fma_f32 v148, v29, v146, v141
	v_rcp_f32_e32 v164, v147
	v_add_f32_e32 v147, 1.0, v162
	v_mul_f32_e32 v148, 0xbfb8aa3b, v148
	v_fma_f32 v162, v25, v146, v137
	v_exp_f32_e32 v148, v148
	v_mul_f32_e32 v162, 0xbfb8aa3b, v162
	v_exp_f32_e32 v162, v162
	v_rcp_f32_e32 v165, v147
	v_add_f32_e32 v147, 1.0, v148
	v_rcp_f32_e32 v148, v147
	v_add_f32_e32 v147, 1.0, v162
	v_fma_f32 v162, v21, v146, v133
	v_mul_f32_e32 v162, 0xbfb8aa3b, v162
	v_fma_f32 v166, v17, v146, v129
	v_exp_f32_e32 v162, v162
	v_mul_f32_e32 v166, 0xbfb8aa3b, v166
	v_exp_f32_e32 v166, v166
	v_rcp_f32_e32 v167, v147
	v_add_f32_e32 v147, 1.0, v162
	v_rcp_f32_e32 v162, v147
	v_add_f32_e32 v147, 1.0, v166
	v_fma_f32 v166, v30, v146, v142
	v_mul_f32_e32 v166, 0xbfb8aa3b, v166
	v_fma_f32 v168, v26, v146, v138
	v_exp_f32_e32 v166, v166
	v_mul_f32_e32 v168, 0xbfb8aa3b, v168
	v_exp_f32_e32 v168, v168
	v_rcp_f32_e32 v169, v147
	v_add_f32_e32 v147, 1.0, v166
	v_rcp_f32_e32 v166, v147
	v_add_f32_e32 v147, 1.0, v168
	v_fma_f32 v168, v22, v146, v134
	v_mul_f32_e32 v168, 0xbfb8aa3b, v168
	v_fma_f32 v170, v18, v146, v130
	v_exp_f32_e32 v168, v168
	v_mul_f32_e32 v170, 0xbfb8aa3b, v170
	v_exp_f32_e32 v170, v170
	v_rcp_f32_e32 v171, v147
	v_add_f32_e32 v147, 1.0, v168
	v_rcp_f32_e32 v168, v147
	v_add_f32_e32 v147, 1.0, v170
	v_fma_f32 v170, v31, v146, v143
	v_mul_f32_e32 v170, 0xbfb8aa3b, v170
	v_fma_f32 v172, v27, v146, v139
	v_exp_f32_e32 v170, v170
	v_mul_f32_e32 v172, 0xbfb8aa3b, v172
	v_exp_f32_e32 v172, v172
	v_rcp_f32_e32 v173, v147
	v_add_f32_e32 v147, 1.0, v170
	v_rcp_f32_e32 v170, v147
	v_add_f32_e32 v147, 1.0, v172
	v_fma_f32 v172, v23, v146, v135
	v_fma_f32 v146, v19, v146, v131
	v_mul_f32_e32 v172, 0xbfb8aa3b, v172
	v_mul_f32_e32 v146, 0xbfb8aa3b, v146
	v_exp_f32_e32 v172, v172
	v_exp_f32_e32 v146, v146
	v_rcp_f32_e32 v174, v147
	v_cvt_pk_bf16_f32 v148, v161, v148
	v_add_f32_e32 v147, 1.0, v172
	v_add_f32_e32 v146, 1.0, v146
	v_rcp_f32_e32 v172, v147
	v_rcp_f32_e32 v175, v146
	v_and_b32_e32 v146, 0xfffffff0, v149
	v_mad_i64_i32 v[146:147], s[2:3], v146, s0, v[156:157]
	v_cvt_pk_bf16_f32 v149, v166, v170
	flat_store_dwordx2 v[146:147], v[148:149]
	v_cvt_pk_bf16_f32 v148, v163, v167
	v_cvt_pk_bf16_f32 v149, v171, v174
	flat_store_dwordx2 v[146:147], v[148:149] offset:512
	v_cvt_pk_bf16_f32 v148, v164, v162
	v_cvt_pk_bf16_f32 v149, v168, v172
	flat_store_dwordx2 v[146:147], v[148:149] offset:1024
	v_cvt_pk_bf16_f32 v148, v165, v169
	v_cvt_pk_bf16_f32 v149, v173, v175
	flat_store_dwordx2 v[146:147], v[148:149] offset:1536
	ds_read_b32 v146, v158 offset:448
	v_or_b32_e32 v147, 0x70, v155
	s_waitcnt lgkmcnt(0)
	v_fma_f32 v128, v12, v146, v128
	v_mul_f32_e32 v128, 0xbfb8aa3b, v128
	v_fma_f32 v141, v1, v146, v141
	v_exp_f32_e32 v128, v128
	v_mul_f32_e32 v141, 0xbfb8aa3b, v141
	v_fma_f32 v137, v5, v146, v137
	v_exp_f32_e32 v141, v141
	v_mul_f32_e32 v137, 0xbfb8aa3b, v137
	v_fma_f32 v133, v9, v146, v133
	v_exp_f32_e32 v137, v137
	v_mul_f32_e32 v133, 0xbfb8aa3b, v133
	v_fma_f32 v129, v13, v146, v129
	v_exp_f32_e32 v133, v133
	v_mul_f32_e32 v129, 0xbfb8aa3b, v129
	v_add_f32_e32 v128, 1.0, v128
	v_exp_f32_e32 v129, v129
	v_rcp_f32_e32 v148, v128
	v_add_f32_e32 v128, 1.0, v141
	v_rcp_f32_e32 v141, v128
	v_add_f32_e32 v128, 1.0, v137
	v_rcp_f32_e32 v137, v128
	v_add_f32_e32 v128, 1.0, v133
	v_rcp_f32_e32 v133, v128
	v_add_f32_e32 v128, 1.0, v129
	v_fma_f32 v129, v2, v146, v142
	v_mul_f32_e32 v129, 0xbfb8aa3b, v129
	v_exp_f32_e32 v129, v129
	v_fma_f32 v138, v6, v146, v138
	v_mul_f32_e32 v138, 0xbfb8aa3b, v138
	v_rcp_f32_e32 v142, v128
	v_add_f32_e32 v128, 1.0, v129
	v_fma_f32 v129, v10, v146, v134
	v_exp_f32_e32 v138, v138
	v_mul_f32_e32 v129, 0xbfb8aa3b, v129
	v_fma_f32 v130, v14, v146, v130
	v_exp_f32_e32 v129, v129
	v_mul_f32_e32 v130, 0xbfb8aa3b, v130
	v_exp_f32_e32 v130, v130
	v_rcp_f32_e32 v149, v128
	v_add_f32_e32 v128, 1.0, v138
	v_fmac_f32_e32 v143, v3, v146
	v_rcp_f32_e32 v134, v128
	v_add_f32_e32 v128, 1.0, v129
	v_mul_f32_e32 v129, 0xbfb8aa3b, v143
	v_fmac_f32_e32 v139, v7, v146
	v_rcp_f32_e32 v138, v128
	v_add_f32_e32 v128, 1.0, v130
	v_exp_f32_e32 v129, v129
	v_mul_f32_e32 v130, 0xbfb8aa3b, v139
	v_exp_f32_e32 v130, v130
	v_fmac_f32_e32 v135, v11, v146
	v_fma_f32 v140, v0, v146, v140
	v_rcp_f32_e32 v139, v128
	v_add_f32_e32 v128, 1.0, v129
	v_mul_f32_e32 v129, 0xbfb8aa3b, v135
	v_fmac_f32_e32 v131, v15, v146
	v_mul_f32_e32 v140, 0xbfb8aa3b, v140
	v_fma_f32 v136, v4, v146, v136
	v_rcp_f32_e32 v143, v128
	v_add_f32_e32 v128, 1.0, v130
	v_exp_f32_e32 v129, v129
	v_mul_f32_e32 v130, 0xbfb8aa3b, v131
	v_exp_f32_e32 v140, v140
	v_mul_f32_e32 v136, 0xbfb8aa3b, v136
	v_fma_f32 v132, v8, v146, v132
	v_exp_f32_e32 v130, v130
	v_exp_f32_e32 v136, v136
	v_mul_f32_e32 v132, 0xbfb8aa3b, v132
	v_exp_f32_e32 v132, v132
	v_rcp_f32_e32 v135, v128
	v_add_f32_e32 v128, 1.0, v129
	v_add_f32_e32 v140, 1.0, v140
	v_rcp_f32_e32 v146, v128
	v_add_f32_e32 v128, 1.0, v130
	v_rcp_f32_e32 v140, v140
	v_add_f32_e32 v136, 1.0, v136
	v_rcp_f32_e32 v155, v128
	v_and_b32_e32 v128, 0xfffffff0, v147
	v_mad_i64_i32 v[128:129], s[2:3], v128, s0, v[156:157]
	v_cvt_pk_bf16_f32 v130, v140, v141
	v_cvt_pk_bf16_f32 v131, v149, v143
	v_rcp_f32_e32 v136, v136
	v_add_f32_e32 v132, 1.0, v132
	flat_store_dwordx2 v[128:129], v[130:131]
	v_cvt_pk_bf16_f32 v130, v136, v137
	v_cvt_pk_bf16_f32 v131, v134, v135
	v_rcp_f32_e32 v132, v132
	flat_store_dwordx2 v[128:129], v[130:131] offset:512
	v_cvt_pk_bf16_f32 v130, v132, v133
	v_cvt_pk_bf16_f32 v131, v138, v146
	flat_store_dwordx2 v[128:129], v[130:131] offset:1024
	v_cvt_pk_bf16_f32 v130, v148, v142
	v_cvt_pk_bf16_f32 v131, v139, v155
	flat_store_dwordx2 v[128:129], v[130:131] offset:1536
	s_mov_b64 s[2:3], 0
